# weight-conversion first item (P0 and phase +8): 32 flat loads -> global loads, so the next item's pointer ds_read no longer waits on them through lgkmcnt
# speedup vs baseline: 1.0054x; 1.0054x over previous
.LBB0_27:
	v_cvt_f32_u32_e32 v2, s31
	s_lshl_b32 s45, s80, 3
	s_add_i32 s38, s42, s45
	s_cmpk_lt_i32 s38, 0x5700
	v_rcp_iflag_f32_e32 v2, v2
	s_cselect_b64 s[24:25], -1, 0
	s_sub_i32 s36, 0, s31
	s_abs_i32 s35, s30
	v_mul_f32_e32 v2, 0x4f7ffffe, v2
	v_cvt_u32_f32_e32 v2, v2
	s_ashr_i32 s34, s30, 31
	v_lshrrev_b32_e32 v1, 5, v170
	v_and_b32_e32 v68, 31, v0
	v_readfirstlane_b32 s37, v2
	s_mul_i32 s36, s36, s37
	s_mul_hi_u32 s36, s37, s36
	s_add_i32 s37, s37, s36
	s_mul_hi_u32 s36, s35, s37
	s_mul_i32 s37, s36, s31
	s_sub_i32 s35, s35, s37
	s_add_i32 s37, s36, 1
	s_sub_i32 s39, s35, s31
	s_cmp_ge_u32 s35, s31
	s_cselect_b32 s36, s37, s36
	s_cselect_b32 s35, s39, s35
	s_add_i32 s37, s36, 1
	s_cmp_ge_u32 s35, s31
	s_cselect_b32 s35, s37, s36
	s_xor_b32 s35, s35, s34
	s_sub_i32 s34, s35, s34
	s_mul_i32 s31, s34, s31
	s_sub_i32 s35, s30, s31
	s_cmpk_gt_i32 s35, 0x7f
	s_cselect_b64 s[30:31], -1, 0
	s_and_b64 s[22:23], s[22:23], s[30:31]
	s_and_b64 s[22:23], s[22:23], exec
	s_cselect_b32 s22, 16, 0
	s_lshl_b32 s46, s35, 5
	s_or_b32 s30, s22, s46
	s_ashr_i32 s31, s30, 31
	s_lshl_b32 s22, s34, 6
	s_lshl_b64 s[30:31], s[30:31], 2
	s_add_u32 s28, s28, s30
	v_mov_b32_e32 v67, 0
	s_addc_u32 s29, s29, s31
	s_ashr_i32 s23, s22, 31
	v_or_b32_e32 v48, s22, v1
	v_lshlrev_b32_e32 v66, 2, v68
	v_lshl_add_u64 v[26:27], s[28:29], 0, v[66:67]
	s_mul_i32 s23, s26, s23
	v_mul_lo_u32 v4, s27, v48
	v_mad_u64_u32 v[2:3], s[28:29], s26, v48, 0
	v_add3_u32 v3, v3, s23, v4
	v_or_b32_e32 v4, 2, v48
	v_mul_lo_u32 v6, s27, v4
	v_mad_u64_u32 v[4:5], s[28:29], s26, v4, 0
	v_add3_u32 v5, v5, s23, v6
	v_or_b32_e32 v6, 4, v48
	v_mul_lo_u32 v8, s27, v6
	v_mad_u64_u32 v[6:7], s[28:29], s26, v6, 0
	v_add3_u32 v7, v7, s23, v8
	v_or_b32_e32 v8, 6, v48
	v_mul_lo_u32 v10, s27, v8
	v_mad_u64_u32 v[8:9], s[28:29], s26, v8, 0
	v_add3_u32 v9, v9, s23, v10
	v_or_b32_e32 v10, 8, v48
	v_mul_lo_u32 v12, s27, v10
	v_mad_u64_u32 v[10:11], s[28:29], s26, v10, 0
	v_add3_u32 v11, v11, s23, v12
	v_or_b32_e32 v12, 10, v48
	v_mul_lo_u32 v14, s27, v12
	v_mad_u64_u32 v[12:13], s[28:29], s26, v12, 0
	v_add3_u32 v13, v13, s23, v14
	v_or_b32_e32 v14, 12, v48
	v_mul_lo_u32 v16, s27, v14
	v_mad_u64_u32 v[14:15], s[28:29], s26, v14, 0
	v_add3_u32 v15, v15, s23, v16
	v_or_b32_e32 v16, 14, v48
	v_mul_lo_u32 v18, s27, v16
	v_mad_u64_u32 v[16:17], s[28:29], s26, v16, 0
	v_lshl_add_u64 v[2:3], v[2:3], 2, v[26:27]
	v_lshl_add_u64 v[4:5], v[4:5], 2, v[26:27]
	v_lshl_add_u64 v[6:7], v[6:7], 2, v[26:27]
	v_lshl_add_u64 v[8:9], v[8:9], 2, v[26:27]
	v_lshl_add_u64 v[10:11], v[10:11], 2, v[26:27]
	v_add3_u32 v17, v17, s23, v18
	v_lshl_add_u64 v[12:13], v[12:13], 2, v[26:27]
	v_lshl_add_u64 v[14:15], v[14:15], 2, v[26:27]
	v_lshl_add_u64 v[16:17], v[16:17], 2, v[26:27]
	global_load_dword v2, v[2:3], off
	s_nop 0
	global_load_dword v3, v[4:5], off
	s_nop 0
	global_load_dword v4, v[6:7], off
	global_load_dword v5, v[8:9], off
	s_nop 0
	global_load_dword v6, v[10:11], off
	global_load_dword v7, v[12:13], off
	global_load_dword v8, v[14:15], off
	global_load_dword v9, v[16:17], off
	v_or_b32_e32 v10, 16, v48
	v_mul_lo_u32 v12, s27, v10
	v_mad_u64_u32 v[10:11], s[28:29], s26, v10, 0
	v_add3_u32 v11, v11, s23, v12
	v_or_b32_e32 v12, 18, v48
	v_mul_lo_u32 v14, s27, v12
	v_mad_u64_u32 v[12:13], s[28:29], s26, v12, 0
	v_add3_u32 v13, v13, s23, v14
	v_or_b32_e32 v14, 20, v48
	v_mul_lo_u32 v16, s27, v14
	v_mad_u64_u32 v[14:15], s[28:29], s26, v14, 0
	v_add3_u32 v15, v15, s23, v16
	v_or_b32_e32 v16, 22, v48
	v_mul_lo_u32 v18, s27, v16
	v_mad_u64_u32 v[16:17], s[28:29], s26, v16, 0
	v_add3_u32 v17, v17, s23, v18
	v_or_b32_e32 v18, 24, v48
	v_mul_lo_u32 v20, s27, v18
	v_mad_u64_u32 v[18:19], s[28:29], s26, v18, 0
	v_add3_u32 v19, v19, s23, v20
	v_or_b32_e32 v20, 26, v48
	v_mul_lo_u32 v22, s27, v20
	v_mad_u64_u32 v[20:21], s[28:29], s26, v20, 0
	v_add3_u32 v21, v21, s23, v22
	v_or_b32_e32 v22, 28, v48
	v_mul_lo_u32 v24, s27, v22
	v_mad_u64_u32 v[22:23], s[28:29], s26, v22, 0
	v_add3_u32 v23, v23, s23, v24
	v_or_b32_e32 v24, 30, v48
	v_mul_lo_u32 v28, s27, v24
	v_mad_u64_u32 v[24:25], s[28:29], s26, v24, 0
	v_lshl_add_u64 v[10:11], v[10:11], 2, v[26:27]
	v_lshl_add_u64 v[12:13], v[12:13], 2, v[26:27]
	v_lshl_add_u64 v[14:15], v[14:15], 2, v[26:27]
	v_lshl_add_u64 v[16:17], v[16:17], 2, v[26:27]
	v_lshl_add_u64 v[18:19], v[18:19], 2, v[26:27]
	v_add3_u32 v25, v25, s23, v28
	v_lshl_add_u64 v[20:21], v[20:21], 2, v[26:27]
	v_lshl_add_u64 v[22:23], v[22:23], 2, v[26:27]
	v_lshl_add_u64 v[24:25], v[24:25], 2, v[26:27]
	global_load_dword v10, v[10:11], off
	s_nop 0
	global_load_dword v11, v[12:13], off
	s_nop 0
	global_load_dword v12, v[14:15], off
	global_load_dword v13, v[16:17], off
	s_nop 0
	global_load_dword v14, v[18:19], off
	global_load_dword v15, v[20:21], off
	global_load_dword v16, v[22:23], off
	global_load_dword v17, v[24:25], off
	v_or_b32_e32 v18, 32, v48
	v_mul_lo_u32 v20, s27, v18
	v_mad_u64_u32 v[18:19], s[28:29], s26, v18, 0
	v_add3_u32 v19, v19, s23, v20
	v_or_b32_e32 v20, 34, v48
	v_mul_lo_u32 v22, s27, v20
	v_mad_u64_u32 v[20:21], s[28:29], s26, v20, 0
	v_add3_u32 v21, v21, s23, v22
	v_or_b32_e32 v22, 36, v48
	v_mul_lo_u32 v24, s27, v22
	v_mad_u64_u32 v[22:23], s[28:29], s26, v22, 0
	v_add3_u32 v23, v23, s23, v24
	v_or_b32_e32 v24, 38, v48
	v_mul_lo_u32 v28, s27, v24
	v_mad_u64_u32 v[24:25], s[28:29], s26, v24, 0
	v_add3_u32 v25, v25, s23, v28
	v_or_b32_e32 v28, 40, v48
	v_mul_lo_u32 v30, s27, v28
	v_mad_u64_u32 v[28:29], s[28:29], s26, v28, 0
	v_add3_u32 v29, v29, s23, v30
	v_or_b32_e32 v30, 42, v48
	v_mul_lo_u32 v32, s27, v30
	v_mad_u64_u32 v[30:31], s[28:29], s26, v30, 0
	v_add3_u32 v31, v31, s23, v32
	v_or_b32_e32 v32, 44, v48
	v_mul_lo_u32 v34, s27, v32
	v_mad_u64_u32 v[32:33], s[28:29], s26, v32, 0
	v_add3_u32 v33, v33, s23, v34
	v_or_b32_e32 v34, 46, v48
	v_mul_lo_u32 v38, s27, v34
	v_mad_u64_u32 v[34:35], s[28:29], s26, v34, 0
	v_lshl_add_u64 v[18:19], v[18:19], 2, v[26:27]
	v_lshl_add_u64 v[20:21], v[20:21], 2, v[26:27]
	v_lshl_add_u64 v[22:23], v[22:23], 2, v[26:27]
	v_lshl_add_u64 v[24:25], v[24:25], 2, v[26:27]
	v_lshl_add_u64 v[28:29], v[28:29], 2, v[26:27]
	v_add3_u32 v35, v35, s23, v38
	v_lshl_add_u64 v[30:31], v[30:31], 2, v[26:27]
	v_lshl_add_u64 v[32:33], v[32:33], 2, v[26:27]
	v_lshl_add_u64 v[34:35], v[34:35], 2, v[26:27]
	global_load_dword v18, v[18:19], off
	s_nop 0
	global_load_dword v19, v[20:21], off
	s_nop 0
	global_load_dword v20, v[22:23], off
	global_load_dword v21, v[24:25], off
	s_nop 0
	global_load_dword v22, v[28:29], off
	global_load_dword v23, v[30:31], off
	global_load_dword v24, v[32:33], off
	global_load_dword v25, v[34:35], off
	v_or_b32_e32 v28, 48, v48
	v_mul_lo_u32 v30, s27, v28
	v_mad_u64_u32 v[28:29], s[28:29], s26, v28, 0
	v_add3_u32 v29, v29, s23, v30
	v_or_b32_e32 v30, 50, v48
	v_mul_lo_u32 v32, s27, v30
	v_mad_u64_u32 v[30:31], s[28:29], s26, v30, 0
	v_add3_u32 v31, v31, s23, v32
	v_lshl_add_u64 v[34:35], v[30:31], 2, v[26:27]
	v_or_b32_e32 v30, 52, v48
	v_mul_lo_u32 v32, s27, v30
	v_mad_u64_u32 v[30:31], s[28:29], s26, v30, 0
	v_add3_u32 v31, v31, s23, v32
	v_lshl_add_u64 v[38:39], v[30:31], 2, v[26:27]
	v_or_b32_e32 v30, 54, v48
	v_mul_lo_u32 v32, s27, v30
	v_mad_u64_u32 v[30:31], s[28:29], s26, v30, 0
	v_add3_u32 v31, v31, s23, v32
	v_lshl_add_u64 v[40:41], v[30:31], 2, v[26:27]
	v_or_b32_e32 v30, 56, v48
	v_mul_lo_u32 v32, s27, v30
	v_mad_u64_u32 v[30:31], s[28:29], s26, v30, 0
	v_add3_u32 v31, v31, s23, v32
	v_lshl_add_u64 v[42:43], v[30:31], 2, v[26:27]
	v_or_b32_e32 v30, 58, v48
	v_mul_lo_u32 v32, s27, v30
	v_mad_u64_u32 v[30:31], s[28:29], s26, v30, 0
	v_add3_u32 v31, v31, s23, v32
	v_lshl_add_u64 v[44:45], v[30:31], 2, v[26:27]
	v_or_b32_e32 v30, 60, v48
	v_mul_lo_u32 v32, s27, v30
	v_mad_u64_u32 v[30:31], s[28:29], s26, v30, 0
	v_add3_u32 v31, v31, s23, v32
	v_lshl_add_u64 v[46:47], v[30:31], 2, v[26:27]
	v_or_b32_e32 v30, 62, v48
	v_mul_lo_u32 v32, s27, v30
	v_mad_u64_u32 v[30:31], s[26:27], s26, v30, 0
	v_lshl_add_u64 v[28:29], v[28:29], 2, v[26:27]
	v_add3_u32 v31, v31, s23, v32
	v_lshl_add_u64 v[48:49], v[30:31], 2, v[26:27]
	global_load_dword v26, v[28:29], off
	global_load_dword v27, v[34:35], off
	s_nop 0
	global_load_dword v28, v[38:39], off
	global_load_dword v29, v[40:41], off
	global_load_dword v30, v[42:43], off
	global_load_dword v31, v[44:45], off
	global_load_dword v32, v[46:47], off
	global_load_dword v33, v[48:49], off
	s_cmpk_gt_i32 s38, 0x56ff
	s_mov_b64 s[26:27], s[20:21]
	s_mov_b32 s48, s22
	s_mov_b32 s47, s43
	s_mov_b32 s49, s46
	s_cbranch_scc1 .LBB0_86
	s_cmpk_lt_i32 s38, 0x3800
	s_cselect_b64 s[28:29], -1, 0
	s_cmpk_gt_i32 s38, 0x37ff
	s_cbranch_scc0 .LBB0_38
	v_mov_b32_e32 v34, 0x3a00
	v_sub_co_u32_e32 v34, vcc, s38, v34
	s_andn2_b64 vcc, exec, vcc
	v_readfirstlane_b32 s23, v34
	s_cbranch_vccz .LBB0_40
	v_mov_b32_e32 v34, 0x3e00
	v_sub_co_u32_e32 v34, vcc, s38, v34
	s_andn2_b64 vcc, exec, vcc
	v_readfirstlane_b32 s26, v34
	s_cbranch_vccz .LBB0_43
	v_mov_b32_e32 v34, 0x4200
	v_sub_co_u32_e32 v34, vcc, s38, v34
	s_andn2_b64 vcc, exec, vcc
	v_readfirstlane_b32 s23, v34
	s_cbranch_vccz .LBB0_45
	v_mov_b32_e32 v34, 0x4600
	v_sub_co_u32_e32 v34, vcc, s38, v34
	s_andn2_b64 vcc, exec, vcc
	v_readfirstlane_b32 s26, v34
	s_cbranch_vccz .LBB0_47
	v_mov_b32_e32 v34, 0x4e00
	v_sub_co_u32_e32 v34, vcc, s38, v34
	s_andn2_b64 vcc, exec, vcc
	v_readfirstlane_b32 s23, v34
	s_cbranch_vccz .LBB0_65
	v_mov_b32_e32 v34, 0x5600
	v_sub_co_u32_e32 v34, vcc, s38, v34
	s_andn2_b64 vcc, exec, vcc
	v_readfirstlane_b32 s30, v34
	s_cbranch_vccz .LBB0_66
	s_add_i32 s23, 0, 0x20500
	v_mov_b32_e32 v34, s23
	ds_read_b64 v[34:35], v34
	s_mov_b64 s[26:27], 0
	s_mov_b32 s23, s30
	s_waitcnt lgkmcnt(0)
	v_readfirstlane_b32 s35, v35
	v_readfirstlane_b32 s34, v34
	s_branch .LBB0_67

.LBB0_1279:
	v_cvt_f32_u32_e32 v2, s59
	s_add_u32 s56, s54, s56
	s_addc_u32 s55, s55, s57
	s_sub_i32 s54, 0, s59
	v_rcp_iflag_f32_e32 v2, v2
	s_abs_i32 s21, s58
	s_ashr_i32 s20, s58, 31
	v_and_b32_e32 v69, 31, v68
	v_mul_f32_e32 v2, 0x4f7ffffe, v2
	v_cvt_u32_f32_e32 v2, v2
	v_bfe_u32 v70, v68, 5, 1
	v_lshlrev_b32_e32 v172, 2, v69
	s_mov_b32 s82, s70
	v_readfirstlane_b32 s57, v2
	s_mul_i32 s54, s54, s57
	s_mul_hi_u32 s54, s57, s54
	s_add_i32 s57, s57, s54
	s_mul_hi_u32 s54, s21, s57
	s_mul_i32 s57, s54, s59
	s_sub_i32 s21, s21, s57
	s_add_i32 s57, s54, 1
	s_sub_i32 s60, s21, s59
	s_cmp_ge_u32 s21, s59
	s_cselect_b32 s54, s57, s54
	s_cselect_b32 s21, s60, s21
	s_add_i32 s57, s54, 1
	s_cmp_ge_u32 s21, s59
	s_cselect_b32 s21, s57, s54
	s_xor_b32 s21, s21, s20
	s_sub_i32 s54, s21, s20
	s_mul_i32 s20, s54, s59
	s_sub_i32 s57, s58, s20
	s_cmpk_gt_i32 s57, 0x7f
	v_readlane_b32 s58, v243, 32
	s_cselect_b64 s[20:21], -1, 0
	v_readlane_b32 s59, v243, 33
	s_and_b64 s[20:21], s[58:59], s[20:21]
	s_and_b64 s[20:21], s[20:21], exec
	s_cselect_b32 s20, 16, 0
	s_lshl_b32 s71, s57, 5
	s_or_b32 s20, s20, s71
	s_ashr_i32 s21, s20, 31
	s_lshl_b32 s54, s54, 6
	s_lshl_b64 s[20:21], s[20:21], 2
	s_add_u32 s20, s56, s20
	s_addc_u32 s21, s55, s21
	v_or_b32_e32 v36, s54, v70
	v_lshl_add_u64 v[34:35], s[20:21], 0, v[172:173]
	s_ashr_i32 s20, s54, 31
	s_mul_i32 s20, s18, s20
	v_mul_lo_u32 v4, s19, v36
	v_mad_u64_u32 v[2:3], s[56:57], s18, v36, 0
	v_add3_u32 v3, v3, s20, v4
	v_lshl_add_u64 v[2:3], v[2:3], 2, v[34:35]
	global_load_dword v2, v[2:3], off
	v_or_b32_e32 v3, 2, v36
	v_mul_lo_u32 v6, s19, v3
	v_mad_u64_u32 v[4:5], s[56:57], s18, v3, 0
	v_add3_u32 v5, v5, s20, v6
	v_lshl_add_u64 v[4:5], v[4:5], 2, v[34:35]
	global_load_dword v3, v[4:5], off
	v_or_b32_e32 v4, 4, v36
	v_mul_lo_u32 v6, s19, v4
	v_mad_u64_u32 v[4:5], s[56:57], s18, v4, 0
	v_add3_u32 v5, v5, s20, v6
	v_lshl_add_u64 v[4:5], v[4:5], 2, v[34:35]
	global_load_dword v4, v[4:5], off
	v_or_b32_e32 v5, 6, v36
	v_mul_lo_u32 v8, s19, v5
	v_mad_u64_u32 v[6:7], s[56:57], s18, v5, 0
	v_add3_u32 v7, v7, s20, v8
	v_lshl_add_u64 v[6:7], v[6:7], 2, v[34:35]
	global_load_dword v5, v[6:7], off
	v_or_b32_e32 v6, 8, v36
	v_mul_lo_u32 v8, s19, v6
	v_mad_u64_u32 v[6:7], s[56:57], s18, v6, 0
	v_add3_u32 v7, v7, s20, v8
	v_lshl_add_u64 v[6:7], v[6:7], 2, v[34:35]
	global_load_dword v6, v[6:7], off
	v_or_b32_e32 v7, 10, v36
	v_mul_lo_u32 v10, s19, v7
	v_mad_u64_u32 v[8:9], s[56:57], s18, v7, 0
	v_add3_u32 v9, v9, s20, v10
	v_lshl_add_u64 v[8:9], v[8:9], 2, v[34:35]
	global_load_dword v7, v[8:9], off
	v_or_b32_e32 v8, 12, v36
	v_mul_lo_u32 v10, s19, v8
	v_mad_u64_u32 v[8:9], s[56:57], s18, v8, 0
	v_add3_u32 v9, v9, s20, v10
	v_lshl_add_u64 v[8:9], v[8:9], 2, v[34:35]
	global_load_dword v8, v[8:9], off
	v_or_b32_e32 v9, 14, v36
	v_mul_lo_u32 v12, s19, v9
	v_mad_u64_u32 v[10:11], s[56:57], s18, v9, 0
	v_add3_u32 v11, v11, s20, v12
	v_lshl_add_u64 v[10:11], v[10:11], 2, v[34:35]
	global_load_dword v9, v[10:11], off
	v_or_b32_e32 v10, 16, v36
	v_mul_lo_u32 v12, s19, v10
	v_mad_u64_u32 v[10:11], s[56:57], s18, v10, 0
	v_add3_u32 v11, v11, s20, v12
	v_lshl_add_u64 v[10:11], v[10:11], 2, v[34:35]
	global_load_dword v10, v[10:11], off
	v_or_b32_e32 v11, 18, v36
	v_mul_lo_u32 v14, s19, v11
	v_mad_u64_u32 v[12:13], s[56:57], s18, v11, 0
	v_add3_u32 v13, v13, s20, v14
	v_lshl_add_u64 v[12:13], v[12:13], 2, v[34:35]
	global_load_dword v11, v[12:13], off
	v_or_b32_e32 v12, 20, v36
	v_mul_lo_u32 v14, s19, v12
	v_mad_u64_u32 v[12:13], s[56:57], s18, v12, 0
	v_add3_u32 v13, v13, s20, v14
	v_lshl_add_u64 v[12:13], v[12:13], 2, v[34:35]
	global_load_dword v12, v[12:13], off
	v_or_b32_e32 v13, 22, v36
	v_mul_lo_u32 v16, s19, v13
	v_mad_u64_u32 v[14:15], s[56:57], s18, v13, 0
	v_add3_u32 v15, v15, s20, v16
	v_lshl_add_u64 v[14:15], v[14:15], 2, v[34:35]
	global_load_dword v13, v[14:15], off
	v_or_b32_e32 v14, 24, v36
	v_mul_lo_u32 v16, s19, v14
	v_mad_u64_u32 v[14:15], s[56:57], s18, v14, 0
	v_add3_u32 v15, v15, s20, v16
	v_lshl_add_u64 v[14:15], v[14:15], 2, v[34:35]
	global_load_dword v14, v[14:15], off
	v_or_b32_e32 v15, 26, v36
	v_mul_lo_u32 v18, s19, v15
	v_mad_u64_u32 v[16:17], s[56:57], s18, v15, 0
	v_add3_u32 v17, v17, s20, v18
	v_lshl_add_u64 v[16:17], v[16:17], 2, v[34:35]
	global_load_dword v15, v[16:17], off
	v_or_b32_e32 v16, 28, v36
	v_mul_lo_u32 v18, s19, v16
	v_mad_u64_u32 v[16:17], s[56:57], s18, v16, 0
	v_add3_u32 v17, v17, s20, v18
	v_lshl_add_u64 v[16:17], v[16:17], 2, v[34:35]
	global_load_dword v16, v[16:17], off
	v_or_b32_e32 v17, 30, v36
	v_mul_lo_u32 v20, s19, v17
	v_mad_u64_u32 v[18:19], s[56:57], s18, v17, 0
	v_add3_u32 v19, v19, s20, v20
	v_lshl_add_u64 v[18:19], v[18:19], 2, v[34:35]
	global_load_dword v17, v[18:19], off
	v_or_b32_e32 v18, 32, v36
	v_mul_lo_u32 v20, s19, v18
	v_mad_u64_u32 v[18:19], s[56:57], s18, v18, 0
	v_add3_u32 v19, v19, s20, v20
	v_lshl_add_u64 v[18:19], v[18:19], 2, v[34:35]
	global_load_dword v18, v[18:19], off
	v_or_b32_e32 v19, 34, v36
	v_mul_lo_u32 v22, s19, v19
	v_mad_u64_u32 v[20:21], s[56:57], s18, v19, 0
	v_add3_u32 v21, v21, s20, v22
	v_lshl_add_u64 v[20:21], v[20:21], 2, v[34:35]
	global_load_dword v19, v[20:21], off
	v_or_b32_e32 v20, 36, v36
	v_mul_lo_u32 v22, s19, v20
	v_mad_u64_u32 v[20:21], s[56:57], s18, v20, 0
	v_add3_u32 v21, v21, s20, v22
	v_lshl_add_u64 v[20:21], v[20:21], 2, v[34:35]
	global_load_dword v20, v[20:21], off
	v_or_b32_e32 v21, 38, v36
	v_mul_lo_u32 v24, s19, v21
	v_mad_u64_u32 v[22:23], s[56:57], s18, v21, 0
	v_add3_u32 v23, v23, s20, v24
	v_lshl_add_u64 v[22:23], v[22:23], 2, v[34:35]
	global_load_dword v21, v[22:23], off
	v_or_b32_e32 v22, 40, v36
	v_mul_lo_u32 v24, s19, v22
	v_mad_u64_u32 v[22:23], s[56:57], s18, v22, 0
	v_add3_u32 v23, v23, s20, v24
	v_lshl_add_u64 v[22:23], v[22:23], 2, v[34:35]
	global_load_dword v22, v[22:23], off
	v_or_b32_e32 v23, 42, v36
	v_mul_lo_u32 v26, s19, v23
	v_mad_u64_u32 v[24:25], s[56:57], s18, v23, 0
	v_add3_u32 v25, v25, s20, v26
	v_lshl_add_u64 v[24:25], v[24:25], 2, v[34:35]
	global_load_dword v23, v[24:25], off
	v_or_b32_e32 v24, 44, v36
	v_mul_lo_u32 v26, s19, v24
	v_mad_u64_u32 v[24:25], s[56:57], s18, v24, 0
	v_add3_u32 v25, v25, s20, v26
	v_lshl_add_u64 v[24:25], v[24:25], 2, v[34:35]
	global_load_dword v24, v[24:25], off
	v_or_b32_e32 v25, 46, v36
	v_mul_lo_u32 v28, s19, v25
	v_mad_u64_u32 v[26:27], s[56:57], s18, v25, 0
	v_add3_u32 v27, v27, s20, v28
	v_lshl_add_u64 v[26:27], v[26:27], 2, v[34:35]
	global_load_dword v25, v[26:27], off
	v_or_b32_e32 v26, 48, v36
	v_mul_lo_u32 v28, s19, v26
	v_mad_u64_u32 v[26:27], s[56:57], s18, v26, 0
	v_add3_u32 v27, v27, s20, v28
	v_lshl_add_u64 v[26:27], v[26:27], 2, v[34:35]
	global_load_dword v26, v[26:27], off
	v_or_b32_e32 v27, 50, v36
	v_mul_lo_u32 v30, s19, v27
	v_mad_u64_u32 v[28:29], s[56:57], s18, v27, 0
	v_add3_u32 v29, v29, s20, v30
	v_lshl_add_u64 v[28:29], v[28:29], 2, v[34:35]
	global_load_dword v27, v[28:29], off
	v_or_b32_e32 v28, 52, v36
	v_mul_lo_u32 v30, s19, v28
	v_mad_u64_u32 v[28:29], s[56:57], s18, v28, 0
	v_add3_u32 v29, v29, s20, v30
	v_lshl_add_u64 v[28:29], v[28:29], 2, v[34:35]
	global_load_dword v28, v[28:29], off
	v_or_b32_e32 v29, 54, v36
	v_mul_lo_u32 v32, s19, v29
	v_mad_u64_u32 v[30:31], s[56:57], s18, v29, 0
	v_add3_u32 v31, v31, s20, v32
	v_lshl_add_u64 v[30:31], v[30:31], 2, v[34:35]
	global_load_dword v29, v[30:31], off
	v_or_b32_e32 v30, 56, v36
	v_mul_lo_u32 v32, s19, v30
	v_mad_u64_u32 v[30:31], s[56:57], s18, v30, 0
	v_add3_u32 v31, v31, s20, v32
	v_lshl_add_u64 v[30:31], v[30:31], 2, v[34:35]
	global_load_dword v30, v[30:31], off
	v_or_b32_e32 v31, 58, v36
	v_mul_lo_u32 v37, s19, v31
	v_mad_u64_u32 v[32:33], s[56:57], s18, v31, 0
	v_add3_u32 v33, v33, s20, v37
	v_lshl_add_u64 v[32:33], v[32:33], 2, v[34:35]
	global_load_dword v31, v[32:33], off
	v_or_b32_e32 v32, 60, v36
	v_mul_lo_u32 v37, s19, v32
	v_mad_u64_u32 v[32:33], s[56:57], s18, v32, 0
	v_add3_u32 v33, v33, s20, v37
	v_lshl_add_u64 v[32:33], v[32:33], 2, v[34:35]
	global_load_dword v32, v[32:33], off
	v_or_b32_e32 v33, 62, v36
	v_mul_lo_u32 v38, s19, v33
	v_mad_u64_u32 v[36:37], s[18:19], s18, v33, 0
	v_add3_u32 v37, v37, s20, v38
	v_lshl_add_u64 v[34:35], v[36:37], 2, v[34:35]
	global_load_dword v33, v[34:35], off
	v_readlane_b32 s18, v243, 56
	v_readlane_b32 s19, v243, 57
	s_andn2_b64 vcc, exec, s[18:19]
	s_mov_b64 s[18:19], s[50:51]
	s_mov_b32 s88, s54
	s_mov_b32 s83, s71
	s_cbranch_vccnz .LBB0_1308
	v_readlane_b32 s18, v243, 60
	v_readlane_b32 s19, v243, 61
	s_mov_b64 s[20:21], -1
	s_and_b64 vcc, exec, s[18:19]
	s_cbranch_vccz .LBB0_1305
	v_readlane_b32 s18, v243, 62
	v_readlane_b32 s19, v243, 63
	s_and_b64 vcc, exec, s[18:19]
	s_cbranch_vccz .LBB0_1303
	v_readlane_b32 s18, v242, 0
	v_readlane_b32 s19, v242, 1
	s_and_b64 vcc, exec, s[18:19]
	s_cbranch_vccz .LBB0_1300
	v_readlane_b32 s18, v242, 2
	v_readlane_b32 s19, v242, 3
	s_and_b64 vcc, exec, s[18:19]
	s_cbranch_vccz .LBB0_1297
	v_readlane_b32 s18, v242, 4
	v_readlane_b32 s19, v242, 5
	s_and_b64 vcc, exec, s[18:19]
	s_cbranch_vccz .LBB0_1294
	v_readlane_b32 s18, v242, 6
	v_readlane_b32 s19, v242, 7
	s_and_b64 vcc, exec, s[18:19]
	s_cbranch_vccz .LBB0_1291
	v_readlane_b32 s20, v242, 8
	v_readlane_b32 s21, v242, 9
	s_mov_b64 s[18:19], -1
	s_and_b64 vcc, exec, s[20:21]
	s_cbranch_vccz .LBB0_1288
	v_readlane_b32 s18, v239, 49
	s_nop 1
	v_mov_b32_e32 v34, s18
	ds_read_b64 v[34:35], v34
	s_mov_b64 s[18:19], 0
	s_waitcnt lgkmcnt(0)
	v_readfirstlane_b32 s59, v35
	v_readfirstlane_b32 s58, v34
